# diff-attention loop pointer advances moved from step tail into PV gaps 8-10 (on v56)
# speedup vs baseline: 1.0030x; 1.0030x over previous
.LBB0_228:
	v_exp_f32_e32 v116, v116
	v_exp_f32_e32 v117, v117
	v_add_f32_e32 v224, v224, v116
	v_cvt_pk_bf16_f32 v175, v116, v117
	v_add_f32_e32 v225, v225, v117
	s_waitcnt lgkmcnt(4)
	v_mfma_f32_32x32x16_bf16 v[98:113], v[182:185], v[154:157], v[98:113]
	ds_read_b128 v[130:133], v254 offset:4096
	ds_read_b128 v[134:137], v254 offset:4608
	v_exp_f32_e32 v118, v118
	v_exp_f32_e32 v119, v119
	v_add_f32_e32 v224, v224, v118
	v_cvt_pk_bf16_f32 v176, v118, v119
	v_add_f32_e32 v225, v225, v119
	s_waitcnt lgkmcnt(5)
	v_mfma_f32_32x32x16_bf16 v[66:81], v[178:181], v[154:157], v[66:81]
	v_exp_f32_e32 v120, v120
	v_exp_f32_e32 v121, v121
	v_add_f32_e32 v224, v224, v120
	v_cvt_pk_bf16_f32 v177, v120, v121
	v_add_f32_e32 v225, v225, v121
	s_waitcnt lgkmcnt(1)
	v_mfma_f32_32x32x16_bf16 v[98:113], v[130:133], v[150:153], v[98:113]
	ds_read_b128 v[138:141], v254 offset:6144
	ds_read_b128 v[142:145], v254 offset:6656
	v_exp_f32_e32 v122, v122
	v_exp_f32_e32 v123, v123
	v_add_f32_e32 v224, v224, v122
	v_cvt_pk_bf16_f32 v130, v122, v123
	v_add_f32_e32 v225, v225, v123
	s_waitcnt lgkmcnt(2)
	v_mfma_f32_32x32x16_bf16 v[66:81], v[134:137], v[150:153], v[66:81]
	v_exp_f32_e32 v124, v124
	v_exp_f32_e32 v125, v125
	v_add_f32_e32 v224, v224, v124
	v_cvt_pk_bf16_f32 v131, v124, v125
	v_add_f32_e32 v225, v225, v125
	s_waitcnt lgkmcnt(1)
	v_mfma_f32_32x32x16_bf16 v[98:113], v[138:141], v[146:149], v[98:113]
	v_exp_f32_e32 v126, v126
	v_exp_f32_e32 v127, v127
	v_add_f32_e32 v224, v224, v126
	v_cvt_pk_bf16_f32 v132, v126, v127
	v_add_f32_e32 v225, v225, v127
	s_waitcnt lgkmcnt(0)
	v_mfma_f32_32x32x16_bf16 v[66:81], v[142:145], v[146:149], v[66:81]
	v_exp_f32_e32 v128, v128
	v_exp_f32_e32 v129, v129
	v_add_f32_e32 v224, v224, v128
	v_cvt_pk_bf16_f32 v133, v128, v129
	v_add_f32_e32 v225, v225, v129
	ds_read_b64_tr_b16 v[134:135], v243 offset:40960
	ds_read_b64_tr_b16 v[136:137], v243 offset:41472
	ds_read_b64_tr_b16 v[138:139], v243 offset:45056
	ds_read_b64_tr_b16 v[140:141], v243 offset:45568
	s_waitcnt lgkmcnt(2)
	v_mfma_f32_32x32x16_bf16 v[50:65], v[174:177], v[134:137], v[50:65]
	ds_read_b64_tr_b16 v[142:143], v243 offset:49152
	ds_read_b64_tr_b16 v[144:145], v243 offset:49664
	v_exp_f32_e32 v82, v82
	v_exp_f32_e32 v83, v83
	v_add_f32_e32 v224, v224, v82
	v_cvt_pk_bf16_f32 v114, v82, v83
	v_add_f32_e32 v225, v225, v83
	s_waitcnt lgkmcnt(2)
	v_mfma_f32_32x32x16_bf16 v[34:49], v[174:177], v[138:141], v[34:49]
	ds_read_b64_tr_b16 v[134:135], v243 offset:53248
	ds_read_b64_tr_b16 v[136:137], v243 offset:53760
	v_exp_f32_e32 v84, v84
	v_exp_f32_e32 v85, v85
	v_add_f32_e32 v224, v224, v84
	v_cvt_pk_bf16_f32 v115, v84, v85
	v_add_f32_e32 v225, v225, v85
	s_waitcnt lgkmcnt(2)
	v_mfma_f32_32x32x16_bf16 v[18:33], v[174:177], v[142:145], v[18:33]
	ds_read_b64_tr_b16 v[138:139], v243 offset:41984
	ds_read_b64_tr_b16 v[140:141], v243 offset:42496
	v_exp_f32_e32 v86, v86
	v_exp_f32_e32 v87, v87
	v_add_f32_e32 v224, v224, v86
	v_cvt_pk_bf16_f32 v116, v86, v87
	v_add_f32_e32 v225, v225, v87
	s_waitcnt lgkmcnt(2)
	v_mfma_f32_32x32x16_bf16 v[2:17], v[174:177], v[134:137], v[2:17]
	ds_read_b64_tr_b16 v[142:143], v243 offset:46080
	ds_read_b64_tr_b16 v[144:145], v243 offset:46592
	v_exp_f32_e32 v88, v88
	v_exp_f32_e32 v89, v89
	v_add_f32_e32 v224, v224, v88
	v_cvt_pk_bf16_f32 v117, v88, v89
	v_add_f32_e32 v225, v225, v89
	s_waitcnt lgkmcnt(2)
	v_mfma_f32_32x32x16_bf16 v[50:65], v[130:133], v[138:141], v[50:65]
	ds_read_b64_tr_b16 v[134:135], v243 offset:50176
	ds_read_b64_tr_b16 v[136:137], v243 offset:50688
	v_exp_f32_e32 v90, v90
	v_exp_f32_e32 v91, v91
	v_add_f32_e32 v224, v224, v90
	v_cvt_pk_bf16_f32 v118, v90, v91
	v_add_f32_e32 v225, v225, v91
	s_waitcnt lgkmcnt(2)
	v_mfma_f32_32x32x16_bf16 v[34:49], v[130:133], v[142:145], v[34:49]
	ds_read_b64_tr_b16 v[138:139], v243 offset:54272
	ds_read_b64_tr_b16 v[140:141], v243 offset:54784
	v_exp_f32_e32 v92, v92
	v_exp_f32_e32 v93, v93
	v_add_f32_e32 v224, v224, v92
	v_cvt_pk_bf16_f32 v119, v92, v93
	v_add_f32_e32 v225, v225, v93
	s_waitcnt lgkmcnt(2)
	v_mfma_f32_32x32x16_bf16 v[18:33], v[130:133], v[134:137], v[18:33]
	ds_read_b64_tr_b16 v[142:143], v243 offset:43008
	ds_read_b64_tr_b16 v[144:145], v243 offset:43520
	v_exp_f32_e32 v94, v94
	v_exp_f32_e32 v95, v95
	v_add_f32_e32 v224, v224, v94
	v_cvt_pk_bf16_f32 v120, v94, v95
	v_add_f32_e32 v225, v225, v95
	s_waitcnt lgkmcnt(2)
	v_mfma_f32_32x32x16_bf16 v[2:17], v[130:133], v[138:141], v[2:17]
	ds_read_b64_tr_b16 v[134:135], v243 offset:47104
	ds_read_b64_tr_b16 v[136:137], v243 offset:47616
	v_exp_f32_e32 v96, v96
	v_exp_f32_e32 v97, v97
	v_add_f32_e32 v224, v224, v96
	v_cvt_pk_bf16_f32 v121, v96, v97
	v_add_f32_e32 v225, v225, v97
	s_waitcnt lgkmcnt(2)
	v_mfma_f32_32x32x16_bf16 v[50:65], v[114:117], v[142:145], v[50:65]
	ds_read_b64_tr_b16 v[128:129], v243 offset:51200
	ds_read_b64_tr_b16 v[130:131], v243 offset:51712
	v_max_f32_e32 v0, v98, v98
	v_max_f32_e32 v0, 0xf149f2ca, v0
	v_max3_f32 v174, v66, s25, v67
	v_lshl_add_u64 v[218:219], v[218:219], 0, s[42:43]
	s_waitcnt lgkmcnt(2)
	v_mfma_f32_32x32x16_bf16 v[34:49], v[114:117], v[134:137], v[34:49]
	ds_read_b64_tr_b16 v[138:139], v243 offset:55296
	ds_read_b64_tr_b16 v[140:141], v243 offset:55808
	v_max3_f32 v0, v0, v99, v100
	v_max3_f32 v174, v174, v68, v69
	v_lshl_add_u64 v[220:221], v[220:221], 0, s[42:43]
	s_waitcnt lgkmcnt(2)
	v_mfma_f32_32x32x16_bf16 v[18:33], v[114:117], v[128:131], v[18:33]
	ds_read_b64_tr_b16 v[132:133], v243 offset:44032
	ds_read_b64_tr_b16 v[134:135], v243 offset:44544
	v_max3_f32 v0, v0, v101, v102
	v_max3_f32 v174, v174, v70, v71
	v_lshl_add_u64 v[222:223], v[222:223], 0, s[42:43]
	s_waitcnt lgkmcnt(2)
	v_mfma_f32_32x32x16_bf16 v[2:17], v[114:117], v[138:141], v[2:17]
	ds_read_b64_tr_b16 v[128:129], v243 offset:48128
	ds_read_b64_tr_b16 v[130:131], v243 offset:48640
	v_max3_f32 v0, v0, v103, v104
	v_max3_f32 v174, v174, v72, v73
	s_waitcnt lgkmcnt(2)
	v_mfma_f32_32x32x16_bf16 v[50:65], v[118:121], v[132:135], v[50:65]
	ds_read_b64_tr_b16 v[114:115], v243 offset:52224
	ds_read_b64_tr_b16 v[116:117], v243 offset:52736
	v_max3_f32 v0, v0, v105, v106
	v_max3_f32 v174, v174, v74, v75
	v_mov_b64_e32 v[136:137], v[228:229]
	v_mov_b64_e32 v[138:139], v[228:229]
	s_waitcnt lgkmcnt(2)
	v_mfma_f32_32x32x16_bf16 v[34:49], v[118:121], v[128:131], v[34:49]
	ds_read_b64_tr_b16 v[132:133], v243 offset:56320
	ds_read_b64_tr_b16 v[134:135], v243 offset:56832
	v_max3_f32 v0, v0, v107, v108
	v_max3_f32 v174, v174, v76, v77
	v_mov_b64_e32 v[140:141], v[228:229]
	v_mov_b64_e32 v[142:143], v[228:229]
	s_waitcnt lgkmcnt(2)
	v_mfma_f32_32x32x16_bf16 v[18:33], v[118:121], v[114:117], v[18:33]
	v_max3_f32 v0, v0, v109, v110
	v_max3_f32 v174, v174, v78, v79
	v_mov_b64_e32 v[144:145], v[228:229]
	v_mov_b64_e32 v[130:131], v[228:229]
	s_waitcnt lgkmcnt(0)
	v_mfma_f32_32x32x16_bf16 v[2:17], v[118:121], v[132:135], v[2:17]
	v_max3_f32 v0, v0, v111, v112
	v_max3_f32 v174, v174, v80, v81
	v_mov_b64_e32 v[132:133], v[228:229]
	v_mov_b64_e32 v[134:135], v[228:229]
	s_add_i32 s36, s36, 2
	v_max3_f32 v114, v0, v113, v174
	s_cmpk_gt_u32 s36, 0x7d
	s_barrier
	s_cbranch_scc1 .LBB0_255
